# write-through (sc1) SwiGLU H stores so the grid barrier release fence has less to flush
# baseline (speedup 1.0000x reference)
; #define PG8_LAS __attribute__((address_space(3)))
; __device__ __forceinline__ unsigned cvt_pk_bf16(float lo, float hi) { unsigned r; asm volatile("v_cvt_pk_bf16_f32 %0, %1, %2" : "=v"(r) : "v"(lo), "v"(hi)); return r; }
;     __device__ __forceinline__ void operator()(const f32x4 (&acc)[2][2][4][2], const Unit& u, int wr, int wc, int fr, int fq, const PG8_LAS float* tab) const {
;         const int row0 = u.pm * BM + wr * 64 + fr, col0 = u.pn * HALF + wc * 32 + 8 * fq;
; #pragma unroll
;         for (int ai = 0; ai < 2; ++ai)
; #pragma unroll
;             for (int m = 0; m < 4; ++m) { const int row = row0 + ai * HALF + m * 16;
;                 const float rs = tab[ai * HALF + wr * 64 + m * 16 + fr];
;                 float hv[8];
; #pragma unroll
;                 for (int n = 0; n < 2; ++n)
; #pragma unroll
;                     for (int j = 0; j < 4; ++j) { const float g = acc[ai][0][m][n][j] * rs, up = acc[ai][1][m][n][j] * rs;
;                         const float e = __builtin_amdgcn_exp2f(g * -1.4426950408889634f);
;                         hv[4 * n + j] = g * up * __builtin_amdgcn_rcpf(1.0f + e); }
;                 u32x4 w; w.x = cvt_pk_bf16(hv[0], hv[1]); w.y = cvt_pk_bf16(hv[2], hv[3]); w.z = cvt_pk_bf16(hv[4], hv[5]); w.w = cvt_pk_bf16(hv[6], hv[7]);
;                 *(u32x4*)(H + (size_t)row * ldh + col0) = w; }
;     }
.LBB0_223:
	v_lshl_add_u32 v148, s59, 10, v144
	ds_read_b32 v150, v148
	v_lshl_add_u32 v140, s29, 7, v145
	v_lshl_add_u32 v147, s28, 8, v142
	s_andn2_b64 vcc, exec, s[0:1]
	v_ashrrev_i32_e32 v141, 31, v140
	s_waitcnt lgkmcnt(0)
	v_mul_f32_e32 v126, v150, v126
	v_mul_f32_e32 v127, v150, v127
	v_mul_f32_e32 v128, v150, v128
	v_mul_f32_e32 v129, v150, v129
	v_mul_f32_e32 v118, v150, v118
	v_mul_f32_e32 v119, v150, v119
	v_mul_f32_e32 v120, v150, v120
	v_mul_f32_e32 v121, v150, v121
	v_mul_f32_e32 v122, v150, v122
	v_mul_f32_e32 v123, v150, v123
	v_mul_f32_e32 v124, v150, v124
	v_mul_f32_e32 v125, v150, v125
	v_mul_f32_e32 v114, v150, v114
	v_mul_f32_e32 v115, v150, v115
	v_mul_f32_e32 v116, v150, v116
	v_mul_f32_e32 v117, v150, v117
	ds_read_b32 v152, v148 offset:64
	v_mul_f32_e32 v122, v126, v122
	v_mul_f32_e32 v123, v127, v123
	v_mul_f32_e32 v124, v128, v124
	v_mul_f32_e32 v125, v129, v125
	v_mul_f32_e32 v114, v118, v114
	v_mul_f32_e32 v115, v119, v115
	v_mul_f32_e32 v116, v120, v116
	v_mul_f32_e32 v117, v121, v117
	v_mul_f32_e32 v126, 0xbfb8aa3b, v126
	v_mul_f32_e32 v127, 0xbfb8aa3b, v127
	v_mul_f32_e32 v128, 0xbfb8aa3b, v128
	v_mul_f32_e32 v129, 0xbfb8aa3b, v129
	v_mul_f32_e32 v118, 0xbfb8aa3b, v118
	v_mul_f32_e32 v119, 0xbfb8aa3b, v119
	v_mul_f32_e32 v120, 0xbfb8aa3b, v120
	v_mul_f32_e32 v121, 0xbfb8aa3b, v121
	v_exp_f32_e32 v126, v126
	v_exp_f32_e32 v127, v127
	v_exp_f32_e32 v128, v128
	v_exp_f32_e32 v129, v129
	v_exp_f32_e32 v118, v118
	v_exp_f32_e32 v119, v119
	v_exp_f32_e32 v120, v120
	v_exp_f32_e32 v121, v121
	v_add_f32_e32 v126, 1.0, v126
	v_add_f32_e32 v127, 1.0, v127
	v_add_f32_e32 v128, 1.0, v128
	v_add_f32_e32 v129, 1.0, v129
	v_add_f32_e32 v118, 1.0, v118
	v_add_f32_e32 v119, 1.0, v119
	v_add_f32_e32 v120, 1.0, v120
	v_add_f32_e32 v121, 1.0, v121
	v_rcp_f32_e32 v126, v126
	v_rcp_f32_e32 v127, v127
	v_rcp_f32_e32 v128, v128
	v_rcp_f32_e32 v129, v129
	v_rcp_f32_e32 v118, v118
	v_rcp_f32_e32 v119, v119
	v_rcp_f32_e32 v120, v120
	v_rcp_f32_e32 v121, v121
	v_mul_f32_e32 v122, v122, v126
	v_mul_f32_e32 v123, v123, v127
	v_mul_f32_e32 v124, v124, v128
	v_mul_f32_e32 v125, v125, v129
	v_mul_f32_e32 v114, v114, v118
	v_mul_f32_e32 v115, v115, v119
	v_mul_f32_e32 v116, v116, v120
	v_mul_f32_e32 v117, v117, v121
	v_cvt_pk_bf16_f32 v126, v122, v123
	v_cvt_pk_bf16_f32 v127, v124, v125
	v_cvt_pk_bf16_f32 v128, v114, v115
	v_cvt_pk_bf16_f32 v129, v116, v117
	v_lshlrev_b64 v[116:117], 1, v[140:141]
	v_mov_b64_e32 v[114:115], s[16:17]
	v_mad_i64_i32 v[120:121], s[28:29], v147, s63, v[114:115]
	v_lshl_add_u64 v[120:121], v[120:121], 0, v[116:117]
	global_store_dwordx4 v[120:121], v[126:129], off sc1
	s_waitcnt lgkmcnt(0)
	v_mul_f32_e32 v110, v152, v110
	v_mul_f32_e32 v111, v152, v111
	v_mul_f32_e32 v112, v152, v112
	v_mul_f32_e32 v113, v152, v113
	v_mul_f32_e32 v102, v152, v102
	v_mul_f32_e32 v103, v152, v103
	v_mul_f32_e32 v104, v152, v104
	v_mul_f32_e32 v105, v152, v105
	v_mul_f32_e32 v106, v152, v106
	v_mul_f32_e32 v107, v152, v107
	v_mul_f32_e32 v108, v152, v108
	v_mul_f32_e32 v109, v152, v109
	v_mul_f32_e32 v98, v152, v98
	v_mul_f32_e32 v99, v152, v99
	v_mul_f32_e32 v100, v152, v100
	v_mul_f32_e32 v101, v152, v101
	ds_read_b32 v150, v148 offset:128
	v_mul_f32_e32 v106, v110, v106
	v_mul_f32_e32 v107, v111, v107
	v_mul_f32_e32 v108, v112, v108
	v_mul_f32_e32 v109, v113, v109
	v_mul_f32_e32 v98, v102, v98
	v_mul_f32_e32 v99, v103, v99
	v_mul_f32_e32 v100, v104, v100
	v_mul_f32_e32 v101, v105, v101
	v_mul_f32_e32 v110, 0xbfb8aa3b, v110
	v_mul_f32_e32 v111, 0xbfb8aa3b, v111
	v_mul_f32_e32 v112, 0xbfb8aa3b, v112
	v_mul_f32_e32 v113, 0xbfb8aa3b, v113
	v_mul_f32_e32 v102, 0xbfb8aa3b, v102
	v_mul_f32_e32 v103, 0xbfb8aa3b, v103
	v_mul_f32_e32 v104, 0xbfb8aa3b, v104
	v_mul_f32_e32 v105, 0xbfb8aa3b, v105
	v_exp_f32_e32 v110, v110
	v_exp_f32_e32 v111, v111
	v_exp_f32_e32 v112, v112
	v_exp_f32_e32 v113, v113
	v_exp_f32_e32 v102, v102
	v_exp_f32_e32 v103, v103
	v_exp_f32_e32 v104, v104
	v_exp_f32_e32 v105, v105
	v_add_f32_e32 v110, 1.0, v110
	v_add_f32_e32 v111, 1.0, v111
	v_add_f32_e32 v112, 1.0, v112
	v_add_f32_e32 v113, 1.0, v113
	v_add_f32_e32 v102, 1.0, v102
	v_add_f32_e32 v103, 1.0, v103
	v_add_f32_e32 v104, 1.0, v104
	v_add_f32_e32 v105, 1.0, v105
	v_rcp_f32_e32 v110, v110
	v_rcp_f32_e32 v111, v111
	v_rcp_f32_e32 v112, v112
	v_rcp_f32_e32 v113, v113
	v_rcp_f32_e32 v102, v102
	v_rcp_f32_e32 v103, v103
	v_rcp_f32_e32 v104, v104
	v_rcp_f32_e32 v105, v105
	v_mul_f32_e32 v106, v106, v110
	v_mul_f32_e32 v107, v107, v111
	v_mul_f32_e32 v108, v108, v112
	v_mul_f32_e32 v109, v109, v113
	v_mul_f32_e32 v98, v98, v102
	v_mul_f32_e32 v99, v99, v103
	v_mul_f32_e32 v100, v100, v104
	v_mul_f32_e32 v101, v101, v105
	v_cvt_pk_bf16_f32 v110, v106, v107
	v_cvt_pk_bf16_f32 v111, v108, v109
	v_cvt_pk_bf16_f32 v112, v98, v99
	v_cvt_pk_bf16_f32 v113, v100, v101
	v_add_u32_e32 v102, 16, v147
	v_mad_i64_i32 v[104:105], s[28:29], v102, s63, v[114:115]
	v_lshl_add_u64 v[104:105], v[104:105], 0, v[116:117]
	global_store_dwordx4 v[104:105], v[110:113], off sc1
	s_waitcnt lgkmcnt(0)
; #define PG8_LAS __attribute__((address_space(3)))
; __device__ __forceinline__ unsigned cvt_pk_bf16(float lo, float hi) { unsigned r; asm volatile("v_cvt_pk_bf16_f32 %0, %1, %2" : "=v"(r) : "v"(lo), "v"(hi)); return r; }
;     __device__ __forceinline__ void operator()(const f32x4 (&acc)[2][2][4][2], const Unit& u, int wr, int wc, int fr, int fq, const PG8_LAS float* tab) const {
;         const int row0 = u.pm * BM + wr * 64 + fr, col0 = u.pn * HALF + wc * 32 + 8 * fq;
; #pragma unroll
;         for (int ai = 0; ai < 2; ++ai)
; #pragma unroll
;             for (int m = 0; m < 4; ++m) { const int row = row0 + ai * HALF + m * 16;
;                 const float rs = tab[ai * HALF + wr * 64 + m * 16 + fr];
;                 float hv[8];
; #pragma unroll
;                 for (int n = 0; n < 2; ++n)
; #pragma unroll
;                     for (int j = 0; j < 4; ++j) { const float g = acc[ai][0][m][n][j] * rs, up = acc[ai][1][m][n][j] * rs;
;                         const float e = __builtin_amdgcn_exp2f(g * -1.4426950408889634f);
;                         hv[4 * n + j] = g * up * __builtin_amdgcn_rcpf(1.0f + e); }
;                 u32x4 w; w.x = cvt_pk_bf16(hv[0], hv[1]); w.y = cvt_pk_bf16(hv[2], hv[3]); w.z = cvt_pk_bf16(hv[4], hv[5]); w.w = cvt_pk_bf16(hv[6], hv[7]);
;                 *(u32x4*)(H + (size_t)row * ldh + col0) = w; }
;     }
	v_mul_f32_e32 v92, v150, v92
	v_mul_f32_e32 v93, v150, v93
	v_mul_f32_e32 v94, v150, v94
	v_mul_f32_e32 v95, v150, v95
	v_mul_f32_e32 v84, v150, v84
	v_mul_f32_e32 v85, v150, v85
	v_mul_f32_e32 v86, v150, v86
	v_mul_f32_e32 v87, v150, v87
	v_mul_f32_e32 v88, v150, v88
	v_mul_f32_e32 v89, v150, v89
	v_mul_f32_e32 v90, v150, v90
	v_mul_f32_e32 v91, v150, v91
	v_mul_f32_e32 v80, v150, v80
	v_mul_f32_e32 v81, v150, v81
	v_mul_f32_e32 v82, v150, v82
	v_mul_f32_e32 v83, v150, v83
	ds_read_b32 v152, v148 offset:192
	v_mul_f32_e32 v88, v92, v88
	v_mul_f32_e32 v89, v93, v89
	v_mul_f32_e32 v90, v94, v90
	v_mul_f32_e32 v91, v95, v91
	v_mul_f32_e32 v80, v84, v80
	v_mul_f32_e32 v81, v85, v81
	v_mul_f32_e32 v82, v86, v82
	v_mul_f32_e32 v83, v87, v83
	v_mul_f32_e32 v92, 0xbfb8aa3b, v92
	v_mul_f32_e32 v93, 0xbfb8aa3b, v93
	v_mul_f32_e32 v94, 0xbfb8aa3b, v94
	v_mul_f32_e32 v95, 0xbfb8aa3b, v95
	v_mul_f32_e32 v84, 0xbfb8aa3b, v84
	v_mul_f32_e32 v85, 0xbfb8aa3b, v85
	v_mul_f32_e32 v86, 0xbfb8aa3b, v86
	v_mul_f32_e32 v87, 0xbfb8aa3b, v87
	v_exp_f32_e32 v92, v92
	v_exp_f32_e32 v93, v93
	v_exp_f32_e32 v94, v94
	v_exp_f32_e32 v95, v95
	v_exp_f32_e32 v84, v84
	v_exp_f32_e32 v85, v85
	v_exp_f32_e32 v86, v86
	v_exp_f32_e32 v87, v87
	v_add_f32_e32 v92, 1.0, v92
	v_add_f32_e32 v93, 1.0, v93
	v_add_f32_e32 v94, 1.0, v94
	v_add_f32_e32 v95, 1.0, v95
	v_add_f32_e32 v84, 1.0, v84
	v_add_f32_e32 v85, 1.0, v85
	v_add_f32_e32 v86, 1.0, v86
	v_add_f32_e32 v87, 1.0, v87
	v_rcp_f32_e32 v92, v92
	v_rcp_f32_e32 v93, v93
	v_rcp_f32_e32 v94, v94
	v_rcp_f32_e32 v95, v95
	v_rcp_f32_e32 v84, v84
	v_rcp_f32_e32 v85, v85
	v_rcp_f32_e32 v86, v86
	v_rcp_f32_e32 v87, v87
	v_mul_f32_e32 v88, v88, v92
	v_mul_f32_e32 v89, v89, v93
	v_mul_f32_e32 v90, v90, v94
	v_mul_f32_e32 v91, v91, v95
	v_mul_f32_e32 v80, v80, v84
	v_mul_f32_e32 v81, v81, v85
	v_mul_f32_e32 v82, v82, v86
	v_mul_f32_e32 v83, v83, v87
	v_cvt_pk_bf16_f32 v92, v88, v89
	v_cvt_pk_bf16_f32 v93, v90, v91
	v_cvt_pk_bf16_f32 v94, v80, v81
	v_cvt_pk_bf16_f32 v95, v82, v83
	v_add_u32_e32 v84, 32, v147
	v_mad_i64_i32 v[86:87], s[28:29], v84, s63, v[114:115]
	v_lshl_add_u64 v[86:87], v[86:87], 0, v[116:117]
	global_store_dwordx4 v[86:87], v[92:95], off sc1
	s_waitcnt lgkmcnt(0)
	v_mul_f32_e32 v76, v152, v76
	v_mul_f32_e32 v77, v152, v77
	v_mul_f32_e32 v78, v152, v78
	v_mul_f32_e32 v79, v152, v79
	v_mul_f32_e32 v68, v152, v68
	v_mul_f32_e32 v69, v152, v69
	v_mul_f32_e32 v70, v152, v70
	v_mul_f32_e32 v71, v152, v71
	v_mul_f32_e32 v72, v152, v72
	v_mul_f32_e32 v73, v152, v73
	v_mul_f32_e32 v74, v152, v74
	v_mul_f32_e32 v75, v152, v75
	v_mul_f32_e32 v64, v152, v64
	v_mul_f32_e32 v65, v152, v65
	v_mul_f32_e32 v66, v152, v66
	v_mul_f32_e32 v67, v152, v67
	ds_read_b32 v150, v148 offset:512
	v_mul_f32_e32 v72, v76, v72
	v_mul_f32_e32 v73, v77, v73
	v_mul_f32_e32 v74, v78, v74
	v_mul_f32_e32 v75, v79, v75
	v_mul_f32_e32 v64, v68, v64
	v_mul_f32_e32 v65, v69, v65
	v_mul_f32_e32 v66, v70, v66
	v_mul_f32_e32 v67, v71, v67
	v_mul_f32_e32 v76, 0xbfb8aa3b, v76
	v_mul_f32_e32 v77, 0xbfb8aa3b, v77
	v_mul_f32_e32 v78, 0xbfb8aa3b, v78
	v_mul_f32_e32 v79, 0xbfb8aa3b, v79
	v_mul_f32_e32 v68, 0xbfb8aa3b, v68
	v_mul_f32_e32 v69, 0xbfb8aa3b, v69
	v_mul_f32_e32 v70, 0xbfb8aa3b, v70
	v_mul_f32_e32 v71, 0xbfb8aa3b, v71
	v_exp_f32_e32 v76, v76
	v_exp_f32_e32 v77, v77
	v_exp_f32_e32 v78, v78
	v_exp_f32_e32 v79, v79
	v_exp_f32_e32 v68, v68
	v_exp_f32_e32 v69, v69
	v_exp_f32_e32 v70, v70
	v_exp_f32_e32 v71, v71
	v_add_f32_e32 v76, 1.0, v76
	v_add_f32_e32 v77, 1.0, v77
	v_add_f32_e32 v78, 1.0, v78
	v_add_f32_e32 v79, 1.0, v79
	v_add_f32_e32 v68, 1.0, v68
	v_add_f32_e32 v69, 1.0, v69
	v_add_f32_e32 v70, 1.0, v70
	v_add_f32_e32 v71, 1.0, v71
	v_rcp_f32_e32 v76, v76
	v_rcp_f32_e32 v77, v77
	v_rcp_f32_e32 v78, v78
	v_rcp_f32_e32 v79, v79
	v_rcp_f32_e32 v68, v68
	v_rcp_f32_e32 v69, v69
	v_rcp_f32_e32 v70, v70
	v_rcp_f32_e32 v71, v71
	v_mul_f32_e32 v72, v72, v76
	v_mul_f32_e32 v73, v73, v77
	v_mul_f32_e32 v74, v74, v78
	v_mul_f32_e32 v75, v75, v79
	v_mul_f32_e32 v64, v64, v68
	v_mul_f32_e32 v65, v65, v69
	v_mul_f32_e32 v66, v66, v70
	v_mul_f32_e32 v67, v67, v71
	v_cvt_pk_bf16_f32 v76, v72, v73
	v_cvt_pk_bf16_f32 v77, v74, v75
	v_cvt_pk_bf16_f32 v78, v64, v65
	v_cvt_pk_bf16_f32 v79, v66, v67
	v_add_u32_e32 v68, 48, v147
	v_mad_i64_i32 v[70:71], s[28:29], v68, s63, v[114:115]
	v_lshl_add_u64 v[70:71], v[70:71], 0, v[116:117]
	global_store_dwordx4 v[70:71], v[76:79], off sc1
	s_waitcnt lgkmcnt(0)
	v_mul_f32_e32 v60, v150, v60
	v_mul_f32_e32 v61, v150, v61
	v_mul_f32_e32 v62, v150, v62
	v_mul_f32_e32 v63, v150, v63
	v_mul_f32_e32 v52, v150, v52
	v_mul_f32_e32 v53, v150, v53
	v_mul_f32_e32 v54, v150, v54
	v_mul_f32_e32 v55, v150, v55
	v_mul_f32_e32 v56, v150, v56
	v_mul_f32_e32 v57, v150, v57
	v_mul_f32_e32 v58, v150, v58
	v_mul_f32_e32 v59, v150, v59
	v_mul_f32_e32 v48, v150, v48
	v_mul_f32_e32 v49, v150, v49
	v_mul_f32_e32 v50, v150, v50
	v_mul_f32_e32 v51, v150, v51
	ds_read_b32 v152, v148 offset:576
	v_mul_f32_e32 v56, v60, v56
	v_mul_f32_e32 v57, v61, v57
	v_mul_f32_e32 v58, v62, v58
	v_mul_f32_e32 v59, v63, v59
	v_mul_f32_e32 v48, v52, v48
	v_mul_f32_e32 v49, v53, v49
	v_mul_f32_e32 v50, v54, v50
	v_mul_f32_e32 v51, v55, v51
	v_mul_f32_e32 v60, 0xbfb8aa3b, v60
	v_mul_f32_e32 v61, 0xbfb8aa3b, v61
	v_mul_f32_e32 v62, 0xbfb8aa3b, v62
	v_mul_f32_e32 v63, 0xbfb8aa3b, v63
	v_mul_f32_e32 v52, 0xbfb8aa3b, v52
	v_mul_f32_e32 v53, 0xbfb8aa3b, v53
	v_mul_f32_e32 v54, 0xbfb8aa3b, v54
	v_mul_f32_e32 v55, 0xbfb8aa3b, v55
	v_exp_f32_e32 v60, v60
	v_exp_f32_e32 v61, v61
	v_exp_f32_e32 v62, v62
	v_exp_f32_e32 v63, v63
	v_exp_f32_e32 v52, v52
	v_exp_f32_e32 v53, v53
	v_exp_f32_e32 v54, v54
	v_exp_f32_e32 v55, v55
	v_add_f32_e32 v60, 1.0, v60
	v_add_f32_e32 v61, 1.0, v61
	v_add_f32_e32 v62, 1.0, v62
	v_add_f32_e32 v63, 1.0, v63
	v_add_f32_e32 v52, 1.0, v52
	v_add_f32_e32 v53, 1.0, v53
	v_add_f32_e32 v54, 1.0, v54
	v_add_f32_e32 v55, 1.0, v55
	v_rcp_f32_e32 v60, v60
	v_rcp_f32_e32 v61, v61
	v_rcp_f32_e32 v62, v62
	v_rcp_f32_e32 v63, v63
	v_rcp_f32_e32 v52, v52
	v_rcp_f32_e32 v53, v53
	v_rcp_f32_e32 v54, v54
	v_rcp_f32_e32 v55, v55
	v_mul_f32_e32 v56, v56, v60
	v_mul_f32_e32 v57, v57, v61
	v_mul_f32_e32 v58, v58, v62
	v_mul_f32_e32 v59, v59, v63
	v_mul_f32_e32 v48, v48, v52
	v_mul_f32_e32 v49, v49, v53
	v_mul_f32_e32 v50, v50, v54
	v_mul_f32_e32 v51, v51, v55
	v_cvt_pk_bf16_f32 v60, v56, v57
	v_cvt_pk_bf16_f32 v61, v58, v59
	v_cvt_pk_bf16_f32 v62, v48, v49
	v_cvt_pk_bf16_f32 v63, v50, v51
	v_add_u32_e32 v52, 128, v147
	v_mad_i64_i32 v[54:55], s[28:29], v52, s63, v[114:115]
	v_lshl_add_u64 v[54:55], v[54:55], 0, v[116:117]
	global_store_dwordx4 v[54:55], v[60:63], off sc1
	s_waitcnt lgkmcnt(0)
; __device__ __forceinline__ unsigned cvt_pk_bf16(float lo, float hi) { unsigned r; asm volatile("v_cvt_pk_bf16_f32 %0, %1, %2" : "=v"(r) : "v"(lo), "v"(hi)); return r; }
; #define PG8_BAR __builtin_amdgcn_s_barrier()
;     __device__ __forceinline__ void operator()(const f32x4 (&acc)[2][2][4][2], const Unit& u, int wr, int wc, int fr, int fq, const PG8_LAS float* tab) const {
;     ...
;             for (int m = 0; m < 4; ++m) { const int row = row0 + ai * HALF + m * 16;
;                 const float rs = tab[ai * HALF + wr * 64 + m * 16 + fr];
;                 float hv[8];
; #pragma unroll
;                 for (int n = 0; n < 2; ++n)
; #pragma unroll
;                     for (int j = 0; j < 4; ++j) { const float g = acc[ai][0][m][n][j] * rs, up = acc[ai][1][m][n][j] * rs;
;                         const float e = __builtin_amdgcn_exp2f(g * -1.4426950408889634f);
;                         hv[4 * n + j] = g * up * __builtin_amdgcn_rcpf(1.0f + e); }
;                 u32x4 w; w.x = cvt_pk_bf16(hv[0], hv[1]); w.y = cvt_pk_bf16(hv[2], hv[3]); w.z = cvt_pk_bf16(hv[4], hv[5]); w.w = cvt_pk_bf16(hv[6], hv[7]);
;                 *(u32x4*)(H + (size_t)row * ldh + col0) = w; }
; template <class Epi, class Sched, bool ALIGN_EPI, bool SP2, int KK, int LDA, int APN>
; __device__ __forceinline__ void gemm_phase(PG8_LAS unsigned char* lds, const Gemm g, const Sched& S, const Epi& E, const int wid) {
;     ...
;         if constexpr (ALIGN_EPI) { if (wr == 1) PG8_BAR; }
	v_mul_f32_e32 v44, v152, v44
	v_mul_f32_e32 v45, v152, v45
	v_mul_f32_e32 v46, v152, v46
	v_mul_f32_e32 v47, v152, v47
	v_mul_f32_e32 v36, v152, v36
	v_mul_f32_e32 v37, v152, v37
	v_mul_f32_e32 v38, v152, v38
	v_mul_f32_e32 v39, v152, v39
	v_mul_f32_e32 v40, v152, v40
	v_mul_f32_e32 v41, v152, v41
	v_mul_f32_e32 v42, v152, v42
	v_mul_f32_e32 v43, v152, v43
	v_mul_f32_e32 v32, v152, v32
	v_mul_f32_e32 v33, v152, v33
	v_mul_f32_e32 v34, v152, v34
	v_mul_f32_e32 v35, v152, v35
	ds_read_b32 v150, v148 offset:640
	v_mul_f32_e32 v40, v44, v40
	v_mul_f32_e32 v41, v45, v41
	v_mul_f32_e32 v42, v46, v42
	v_mul_f32_e32 v43, v47, v43
	v_mul_f32_e32 v32, v36, v32
	v_mul_f32_e32 v33, v37, v33
	v_mul_f32_e32 v34, v38, v34
	v_mul_f32_e32 v35, v39, v35
	v_mul_f32_e32 v44, 0xbfb8aa3b, v44
	v_mul_f32_e32 v45, 0xbfb8aa3b, v45
	v_mul_f32_e32 v46, 0xbfb8aa3b, v46
	v_mul_f32_e32 v47, 0xbfb8aa3b, v47
	v_mul_f32_e32 v36, 0xbfb8aa3b, v36
	v_mul_f32_e32 v37, 0xbfb8aa3b, v37
	v_mul_f32_e32 v38, 0xbfb8aa3b, v38
	v_mul_f32_e32 v39, 0xbfb8aa3b, v39
	v_exp_f32_e32 v44, v44
	v_exp_f32_e32 v45, v45
	v_exp_f32_e32 v46, v46
	v_exp_f32_e32 v47, v47
	v_exp_f32_e32 v36, v36
	v_exp_f32_e32 v37, v37
	v_exp_f32_e32 v38, v38
	v_exp_f32_e32 v39, v39
	v_add_f32_e32 v44, 1.0, v44
	v_add_f32_e32 v45, 1.0, v45
	v_add_f32_e32 v46, 1.0, v46
	v_add_f32_e32 v47, 1.0, v47
	v_add_f32_e32 v36, 1.0, v36
	v_add_f32_e32 v37, 1.0, v37
	v_add_f32_e32 v38, 1.0, v38
	v_add_f32_e32 v39, 1.0, v39
	v_rcp_f32_e32 v44, v44
	v_rcp_f32_e32 v45, v45
	v_rcp_f32_e32 v46, v46
	v_rcp_f32_e32 v47, v47
	v_rcp_f32_e32 v36, v36
	v_rcp_f32_e32 v37, v37
	v_rcp_f32_e32 v38, v38
	v_rcp_f32_e32 v39, v39
	v_mul_f32_e32 v40, v40, v44
	v_mul_f32_e32 v41, v41, v45
	v_mul_f32_e32 v42, v42, v46
	v_mul_f32_e32 v43, v43, v47
	v_mul_f32_e32 v32, v32, v36
	v_mul_f32_e32 v33, v33, v37
	v_mul_f32_e32 v34, v34, v38
	v_mul_f32_e32 v35, v35, v39
	v_cvt_pk_bf16_f32 v44, v40, v41
	v_cvt_pk_bf16_f32 v45, v42, v43
	v_cvt_pk_bf16_f32 v46, v32, v33
	v_cvt_pk_bf16_f32 v47, v34, v35
	v_add_u32_e32 v36, 144, v147
	v_mad_i64_i32 v[38:39], s[28:29], v36, s63, v[114:115]
	v_lshl_add_u64 v[38:39], v[38:39], 0, v[116:117]
	global_store_dwordx4 v[38:39], v[44:47], off sc1
	s_waitcnt lgkmcnt(0)
	v_mul_f32_e32 v28, v150, v28
	v_mul_f32_e32 v29, v150, v29
	v_mul_f32_e32 v30, v150, v30
	v_mul_f32_e32 v31, v150, v31
	v_mul_f32_e32 v20, v150, v20
	v_mul_f32_e32 v21, v150, v21
	v_mul_f32_e32 v22, v150, v22
	v_mul_f32_e32 v23, v150, v23
	v_mul_f32_e32 v24, v150, v24
	v_mul_f32_e32 v25, v150, v25
	v_mul_f32_e32 v26, v150, v26
	v_mul_f32_e32 v27, v150, v27
	v_mul_f32_e32 v16, v150, v16
	v_mul_f32_e32 v17, v150, v17
	v_mul_f32_e32 v18, v150, v18
	v_mul_f32_e32 v19, v150, v19
	ds_read_b32 v152, v148 offset:704
	v_mul_f32_e32 v24, v28, v24
	v_mul_f32_e32 v25, v29, v25
	v_mul_f32_e32 v26, v30, v26
	v_mul_f32_e32 v27, v31, v27
	v_mul_f32_e32 v16, v20, v16
	v_mul_f32_e32 v17, v21, v17
	v_mul_f32_e32 v18, v22, v18
	v_mul_f32_e32 v19, v23, v19
	v_mul_f32_e32 v28, 0xbfb8aa3b, v28
	v_mul_f32_e32 v29, 0xbfb8aa3b, v29
	v_mul_f32_e32 v30, 0xbfb8aa3b, v30
	v_mul_f32_e32 v31, 0xbfb8aa3b, v31
	v_mul_f32_e32 v20, 0xbfb8aa3b, v20
	v_mul_f32_e32 v21, 0xbfb8aa3b, v21
	v_mul_f32_e32 v22, 0xbfb8aa3b, v22
	v_mul_f32_e32 v23, 0xbfb8aa3b, v23
	v_exp_f32_e32 v28, v28
	v_exp_f32_e32 v29, v29
	v_exp_f32_e32 v30, v30
	v_exp_f32_e32 v31, v31
	v_exp_f32_e32 v20, v20
	v_exp_f32_e32 v21, v21
	v_exp_f32_e32 v22, v22
	v_exp_f32_e32 v23, v23
	v_add_f32_e32 v28, 1.0, v28
	v_add_f32_e32 v29, 1.0, v29
	v_add_f32_e32 v30, 1.0, v30
	v_add_f32_e32 v31, 1.0, v31
	v_add_f32_e32 v20, 1.0, v20
	v_add_f32_e32 v21, 1.0, v21
	v_add_f32_e32 v22, 1.0, v22
	v_add_f32_e32 v23, 1.0, v23
	v_rcp_f32_e32 v28, v28
	v_rcp_f32_e32 v29, v29
	v_rcp_f32_e32 v30, v30
	v_rcp_f32_e32 v31, v31
	v_rcp_f32_e32 v20, v20
	v_rcp_f32_e32 v21, v21
	v_rcp_f32_e32 v22, v22
	v_rcp_f32_e32 v23, v23
	v_mul_f32_e32 v24, v24, v28
	v_mul_f32_e32 v25, v25, v29
	v_mul_f32_e32 v26, v26, v30
	v_mul_f32_e32 v27, v27, v31
	v_mul_f32_e32 v16, v16, v20
	v_mul_f32_e32 v17, v17, v21
	v_mul_f32_e32 v18, v18, v22
	v_mul_f32_e32 v19, v19, v23
	v_cvt_pk_bf16_f32 v28, v24, v25
	v_cvt_pk_bf16_f32 v29, v26, v27
	v_cvt_pk_bf16_f32 v30, v16, v17
	v_cvt_pk_bf16_f32 v31, v18, v19
	v_add_u32_e32 v20, 160, v147
	v_mad_i64_i32 v[22:23], s[28:29], v20, s63, v[114:115]
	v_lshl_add_u64 v[22:23], v[22:23], 0, v[116:117]
	global_store_dwordx4 v[22:23], v[28:31], off sc1
	s_waitcnt lgkmcnt(0)
	v_mul_f32_e32 v12, v152, v12
	v_mul_f32_e32 v13, v152, v13
	v_mul_f32_e32 v14, v152, v14
	v_mul_f32_e32 v15, v152, v15
	v_mul_f32_e32 v4, v152, v4
	v_mul_f32_e32 v5, v152, v5
	v_mul_f32_e32 v6, v152, v6
	v_mul_f32_e32 v7, v152, v7
	v_mul_f32_e32 v8, v152, v8
	v_mul_f32_e32 v9, v152, v9
	v_mul_f32_e32 v10, v152, v10
	v_mul_f32_e32 v11, v152, v11
	v_mul_f32_e32 v0, v152, v0
	v_mul_f32_e32 v1, v152, v1
	v_mul_f32_e32 v2, v152, v2
	v_mul_f32_e32 v3, v152, v3
	v_mul_f32_e32 v8, v12, v8
	v_mul_f32_e32 v9, v13, v9
	v_mul_f32_e32 v10, v14, v10
	v_mul_f32_e32 v11, v15, v11
	v_mul_f32_e32 v0, v4, v0
	v_mul_f32_e32 v1, v5, v1
	v_mul_f32_e32 v2, v6, v2
	v_mul_f32_e32 v3, v7, v3
	v_mul_f32_e32 v12, 0xbfb8aa3b, v12
	v_mul_f32_e32 v13, 0xbfb8aa3b, v13
	v_mul_f32_e32 v14, 0xbfb8aa3b, v14
	v_mul_f32_e32 v15, 0xbfb8aa3b, v15
	v_mul_f32_e32 v4, 0xbfb8aa3b, v4
	v_mul_f32_e32 v5, 0xbfb8aa3b, v5
	v_mul_f32_e32 v6, 0xbfb8aa3b, v6
	v_mul_f32_e32 v7, 0xbfb8aa3b, v7
	v_exp_f32_e32 v12, v12
	v_exp_f32_e32 v13, v13
	v_exp_f32_e32 v14, v14
	v_exp_f32_e32 v15, v15
	v_exp_f32_e32 v4, v4
	v_exp_f32_e32 v5, v5
	v_exp_f32_e32 v6, v6
	v_exp_f32_e32 v7, v7
	v_add_f32_e32 v12, 1.0, v12
	v_add_f32_e32 v13, 1.0, v13
	v_add_f32_e32 v14, 1.0, v14
	v_add_f32_e32 v15, 1.0, v15
	v_add_f32_e32 v4, 1.0, v4
	v_add_f32_e32 v5, 1.0, v5
	v_add_f32_e32 v6, 1.0, v6
	v_add_f32_e32 v7, 1.0, v7
	v_rcp_f32_e32 v12, v12
	v_rcp_f32_e32 v13, v13
	v_rcp_f32_e32 v14, v14
	v_rcp_f32_e32 v15, v15
	v_rcp_f32_e32 v4, v4
	v_rcp_f32_e32 v5, v5
	v_rcp_f32_e32 v6, v6
	v_rcp_f32_e32 v7, v7
	v_mul_f32_e32 v8, v8, v12
	v_mul_f32_e32 v9, v9, v13
	v_mul_f32_e32 v10, v10, v14
	v_mul_f32_e32 v11, v11, v15
	v_mul_f32_e32 v0, v0, v4
	v_mul_f32_e32 v1, v1, v5
	v_mul_f32_e32 v2, v2, v6
	v_mul_f32_e32 v3, v3, v7
	v_cvt_pk_bf16_f32 v12, v8, v9
	v_cvt_pk_bf16_f32 v13, v10, v11
	v_cvt_pk_bf16_f32 v14, v0, v1
	v_cvt_pk_bf16_f32 v15, v2, v3
	v_add_u32_e32 v4, 176, v147
	v_mad_i64_i32 v[6:7], s[28:29], v4, s63, v[114:115]
	v_lshl_add_u64 v[6:7], v[6:7], 0, v[116:117]
	s_mov_b64 s[28:29], -1
	global_store_dwordx4 v[6:7], v[12:15], off sc1
	s_cbranch_vccnz .LBB0_216
	s_andn2_b64 vcc, exec, s[14:15]
	s_cbranch_vccnz .LBB0_215
	s_barrier
	s_branch .LBB0_215

; __device__ __forceinline__ unsigned cvt_pk_bf16(float lo, float hi) { unsigned r; asm volatile("v_cvt_pk_bf16_f32 %0, %1, %2" : "=v"(r) : "v"(lo), "v"(hi)); return r; }
;     __device__ __forceinline__ void operator()(const f32x4 (&acc)[2][2][4][2], const Unit& u, int wr, int wc, int fr, int fq, const PG8_LAS float* tab) const {
;         const int row0 = u.pm * BM + wr * 64 + fr, col0 = u.pn * HALF + wc * 32 + 8 * fq;
; #pragma unroll
;         for (int ai = 0; ai < 2; ++ai)
; #pragma unroll
;             for (int m = 0; m < 4; ++m) { const int row = row0 + ai * HALF + m * 16;
;                 const float rs = tab[ai * HALF + wr * 64 + m * 16 + fr];
;                 float hv[8];
; #pragma unroll
;                 for (int n = 0; n < 2; ++n)
; #pragma unroll
;                     for (int j = 0; j < 4; ++j) { const float g = acc[ai][0][m][n][j] * rs, up = acc[ai][1][m][n][j] * rs;
;                         const float e = __builtin_amdgcn_exp2f(g * -1.4426950408889634f);
;                         hv[4 * n + j] = g * up * __builtin_amdgcn_rcpf(1.0f + e); }
;                 u32x4 w; w.x = cvt_pk_bf16(hv[0], hv[1]); w.y = cvt_pk_bf16(hv[2], hv[3]); w.z = cvt_pk_bf16(hv[4], hv[5]); w.w = cvt_pk_bf16(hv[6], hv[7]);
;                 *(u32x4*)(H + (size_t)row * ldh + col0) = w; }
.LBB0_782:
	v_lshl_add_u32 v148, s50, 10, v144
	ds_read_b32 v150, v148
	v_lshl_add_u32 v140, s29, 7, v145
	v_lshl_add_u32 v147, s28, 8, v142
	s_andn2_b64 vcc, exec, s[0:1]
	v_ashrrev_i32_e32 v141, 31, v140
	v_readlane_b32 s58, v255, 23
	v_readlane_b32 s59, v255, 24
	s_waitcnt lgkmcnt(0)
	v_mul_f32_e32 v126, v150, v126
	v_mul_f32_e32 v127, v150, v127
	v_mul_f32_e32 v128, v150, v128
	v_mul_f32_e32 v129, v150, v129
	v_mul_f32_e32 v118, v150, v118
	v_mul_f32_e32 v119, v150, v119
	v_mul_f32_e32 v120, v150, v120
	v_mul_f32_e32 v121, v150, v121
	v_mul_f32_e32 v122, v150, v122
	v_mul_f32_e32 v123, v150, v123
	v_mul_f32_e32 v124, v150, v124
	v_mul_f32_e32 v125, v150, v125
	v_mul_f32_e32 v114, v150, v114
	v_mul_f32_e32 v115, v150, v115
	v_mul_f32_e32 v116, v150, v116
	v_mul_f32_e32 v117, v150, v117
	ds_read_b32 v152, v148 offset:64
	v_mul_f32_e32 v122, v126, v122
	v_mul_f32_e32 v123, v127, v123
	v_mul_f32_e32 v124, v128, v124
	v_mul_f32_e32 v125, v129, v125
	v_mul_f32_e32 v114, v118, v114
	v_mul_f32_e32 v115, v119, v115
	v_mul_f32_e32 v116, v120, v116
	v_mul_f32_e32 v117, v121, v117
	v_mul_f32_e32 v126, 0xbfb8aa3b, v126
	v_mul_f32_e32 v127, 0xbfb8aa3b, v127
	v_mul_f32_e32 v128, 0xbfb8aa3b, v128
	v_mul_f32_e32 v129, 0xbfb8aa3b, v129
	v_mul_f32_e32 v118, 0xbfb8aa3b, v118
	v_mul_f32_e32 v119, 0xbfb8aa3b, v119
	v_mul_f32_e32 v120, 0xbfb8aa3b, v120
	v_mul_f32_e32 v121, 0xbfb8aa3b, v121
	v_exp_f32_e32 v126, v126
	v_exp_f32_e32 v127, v127
	v_exp_f32_e32 v128, v128
	v_exp_f32_e32 v129, v129
	v_exp_f32_e32 v118, v118
	v_exp_f32_e32 v119, v119
	v_exp_f32_e32 v120, v120
	v_exp_f32_e32 v121, v121
	v_add_f32_e32 v126, 1.0, v126
	v_add_f32_e32 v127, 1.0, v127
	v_add_f32_e32 v128, 1.0, v128
	v_add_f32_e32 v129, 1.0, v129
	v_add_f32_e32 v118, 1.0, v118
	v_add_f32_e32 v119, 1.0, v119
	v_add_f32_e32 v120, 1.0, v120
	v_add_f32_e32 v121, 1.0, v121
	v_rcp_f32_e32 v126, v126
	v_rcp_f32_e32 v127, v127
	v_rcp_f32_e32 v128, v128
	v_rcp_f32_e32 v129, v129
	v_rcp_f32_e32 v118, v118
	v_rcp_f32_e32 v119, v119
	v_rcp_f32_e32 v120, v120
	v_rcp_f32_e32 v121, v121
	v_mul_f32_e32 v122, v122, v126
	v_mul_f32_e32 v123, v123, v127
	v_mul_f32_e32 v124, v124, v128
	v_mul_f32_e32 v125, v125, v129
	v_mul_f32_e32 v114, v114, v118
	v_mul_f32_e32 v115, v115, v119
	v_mul_f32_e32 v116, v116, v120
	v_mul_f32_e32 v117, v117, v121
	v_cvt_pk_bf16_f32 v126, v122, v123
	v_cvt_pk_bf16_f32 v127, v124, v125
	v_cvt_pk_bf16_f32 v128, v114, v115
	v_cvt_pk_bf16_f32 v129, v116, v117
	v_lshlrev_b64 v[116:117], 1, v[140:141]
	v_mov_b64_e32 v[114:115], s[16:17]
	v_mad_i64_i32 v[120:121], s[28:29], v147, s63, v[114:115]
	v_lshl_add_u64 v[120:121], v[120:121], 0, v[116:117]
	global_store_dwordx4 v[120:121], v[126:129], off sc1
	s_waitcnt lgkmcnt(0)
	v_mul_f32_e32 v110, v152, v110
	v_mul_f32_e32 v111, v152, v111
	v_mul_f32_e32 v112, v152, v112
	v_mul_f32_e32 v113, v152, v113
	v_mul_f32_e32 v102, v152, v102
	v_mul_f32_e32 v103, v152, v103
	v_mul_f32_e32 v104, v152, v104
	v_mul_f32_e32 v105, v152, v105
	v_mul_f32_e32 v106, v152, v106
	v_mul_f32_e32 v107, v152, v107
	v_mul_f32_e32 v108, v152, v108
	v_mul_f32_e32 v109, v152, v109
	v_mul_f32_e32 v98, v152, v98
	v_mul_f32_e32 v99, v152, v99
	v_mul_f32_e32 v100, v152, v100
	v_mul_f32_e32 v101, v152, v101
	ds_read_b32 v150, v148 offset:128
	v_mul_f32_e32 v106, v110, v106
	v_mul_f32_e32 v107, v111, v107
	v_mul_f32_e32 v108, v112, v108
	v_mul_f32_e32 v109, v113, v109
	v_mul_f32_e32 v98, v102, v98
	v_mul_f32_e32 v99, v103, v99
	v_mul_f32_e32 v100, v104, v100
	v_mul_f32_e32 v101, v105, v101
	v_mul_f32_e32 v110, 0xbfb8aa3b, v110
	v_mul_f32_e32 v111, 0xbfb8aa3b, v111
	v_mul_f32_e32 v112, 0xbfb8aa3b, v112
	v_mul_f32_e32 v113, 0xbfb8aa3b, v113
	v_mul_f32_e32 v102, 0xbfb8aa3b, v102
	v_mul_f32_e32 v103, 0xbfb8aa3b, v103
	v_mul_f32_e32 v104, 0xbfb8aa3b, v104
	v_mul_f32_e32 v105, 0xbfb8aa3b, v105
	v_exp_f32_e32 v110, v110
	v_exp_f32_e32 v111, v111
	v_exp_f32_e32 v112, v112
	v_exp_f32_e32 v113, v113
	v_exp_f32_e32 v102, v102
	v_exp_f32_e32 v103, v103
	v_exp_f32_e32 v104, v104
	v_exp_f32_e32 v105, v105
	v_add_f32_e32 v110, 1.0, v110
	v_add_f32_e32 v111, 1.0, v111
	v_add_f32_e32 v112, 1.0, v112
	v_add_f32_e32 v113, 1.0, v113
	v_add_f32_e32 v102, 1.0, v102
	v_add_f32_e32 v103, 1.0, v103
	v_add_f32_e32 v104, 1.0, v104
	v_add_f32_e32 v105, 1.0, v105
	v_rcp_f32_e32 v110, v110
	v_rcp_f32_e32 v111, v111
	v_rcp_f32_e32 v112, v112
	v_rcp_f32_e32 v113, v113
	v_rcp_f32_e32 v102, v102
	v_rcp_f32_e32 v103, v103
	v_rcp_f32_e32 v104, v104
	v_rcp_f32_e32 v105, v105
	v_mul_f32_e32 v106, v106, v110
	v_mul_f32_e32 v107, v107, v111
	v_mul_f32_e32 v108, v108, v112
	v_mul_f32_e32 v109, v109, v113
	v_mul_f32_e32 v98, v98, v102
	v_mul_f32_e32 v99, v99, v103
	v_mul_f32_e32 v100, v100, v104
	v_mul_f32_e32 v101, v101, v105
	v_cvt_pk_bf16_f32 v110, v106, v107
	v_cvt_pk_bf16_f32 v111, v108, v109
	v_cvt_pk_bf16_f32 v112, v98, v99
	v_cvt_pk_bf16_f32 v113, v100, v101
	v_add_u32_e32 v102, 16, v147
	v_mad_i64_i32 v[104:105], s[28:29], v102, s63, v[114:115]
	v_lshl_add_u64 v[104:105], v[104:105], 0, v[116:117]
	global_store_dwordx4 v[104:105], v[110:113], off sc1
	s_waitcnt lgkmcnt(0)
; __device__ __forceinline__ unsigned cvt_pk_bf16(float lo, float hi) { unsigned r; asm volatile("v_cvt_pk_bf16_f32 %0, %1, %2" : "=v"(r) : "v"(lo), "v"(hi)); return r; }
;     __device__ __forceinline__ void operator()(const f32x4 (&acc)[2][2][4][2], const Unit& u, int wr, int wc, int fr, int fq, const PG8_LAS float* tab) const {
;     ...
;             for (int m = 0; m < 4; ++m) { const int row = row0 + ai * HALF + m * 16;
;                 const float rs = tab[ai * HALF + wr * 64 + m * 16 + fr];
;                 float hv[8];
; #pragma unroll
;                 for (int n = 0; n < 2; ++n)
; #pragma unroll
;                     for (int j = 0; j < 4; ++j) { const float g = acc[ai][0][m][n][j] * rs, up = acc[ai][1][m][n][j] * rs;
;                         const float e = __builtin_amdgcn_exp2f(g * -1.4426950408889634f);
;                         hv[4 * n + j] = g * up * __builtin_amdgcn_rcpf(1.0f + e); }
;                 u32x4 w; w.x = cvt_pk_bf16(hv[0], hv[1]); w.y = cvt_pk_bf16(hv[2], hv[3]); w.z = cvt_pk_bf16(hv[4], hv[5]); w.w = cvt_pk_bf16(hv[6], hv[7]);
;                 *(u32x4*)(H + (size_t)row * ldh + col0) = w; }
	v_mul_f32_e32 v92, v150, v92
	v_mul_f32_e32 v93, v150, v93
	v_mul_f32_e32 v94, v150, v94
	v_mul_f32_e32 v95, v150, v95
	v_mul_f32_e32 v84, v150, v84
	v_mul_f32_e32 v85, v150, v85
	v_mul_f32_e32 v86, v150, v86
	v_mul_f32_e32 v87, v150, v87
	v_mul_f32_e32 v88, v150, v88
	v_mul_f32_e32 v89, v150, v89
	v_mul_f32_e32 v90, v150, v90
	v_mul_f32_e32 v91, v150, v91
	v_mul_f32_e32 v80, v150, v80
	v_mul_f32_e32 v81, v150, v81
	v_mul_f32_e32 v82, v150, v82
	v_mul_f32_e32 v83, v150, v83
	ds_read_b32 v152, v148 offset:192
	v_mul_f32_e32 v88, v92, v88
	v_mul_f32_e32 v89, v93, v89
	v_mul_f32_e32 v90, v94, v90
	v_mul_f32_e32 v91, v95, v91
	v_mul_f32_e32 v80, v84, v80
	v_mul_f32_e32 v81, v85, v81
	v_mul_f32_e32 v82, v86, v82
	v_mul_f32_e32 v83, v87, v83
	v_mul_f32_e32 v92, 0xbfb8aa3b, v92
	v_mul_f32_e32 v93, 0xbfb8aa3b, v93
	v_mul_f32_e32 v94, 0xbfb8aa3b, v94
	v_mul_f32_e32 v95, 0xbfb8aa3b, v95
	v_mul_f32_e32 v84, 0xbfb8aa3b, v84
	v_mul_f32_e32 v85, 0xbfb8aa3b, v85
	v_mul_f32_e32 v86, 0xbfb8aa3b, v86
	v_mul_f32_e32 v87, 0xbfb8aa3b, v87
	v_exp_f32_e32 v92, v92
	v_exp_f32_e32 v93, v93
	v_exp_f32_e32 v94, v94
	v_exp_f32_e32 v95, v95
	v_exp_f32_e32 v84, v84
	v_exp_f32_e32 v85, v85
	v_exp_f32_e32 v86, v86
	v_exp_f32_e32 v87, v87
	v_add_f32_e32 v92, 1.0, v92
	v_add_f32_e32 v93, 1.0, v93
	v_add_f32_e32 v94, 1.0, v94
	v_add_f32_e32 v95, 1.0, v95
	v_add_f32_e32 v84, 1.0, v84
	v_add_f32_e32 v85, 1.0, v85
	v_add_f32_e32 v86, 1.0, v86
	v_add_f32_e32 v87, 1.0, v87
	v_rcp_f32_e32 v92, v92
	v_rcp_f32_e32 v93, v93
	v_rcp_f32_e32 v94, v94
	v_rcp_f32_e32 v95, v95
	v_rcp_f32_e32 v84, v84
	v_rcp_f32_e32 v85, v85
	v_rcp_f32_e32 v86, v86
	v_rcp_f32_e32 v87, v87
	v_mul_f32_e32 v88, v88, v92
	v_mul_f32_e32 v89, v89, v93
	v_mul_f32_e32 v90, v90, v94
	v_mul_f32_e32 v91, v91, v95
	v_mul_f32_e32 v80, v80, v84
	v_mul_f32_e32 v81, v81, v85
	v_mul_f32_e32 v82, v82, v86
	v_mul_f32_e32 v83, v83, v87
	v_cvt_pk_bf16_f32 v92, v88, v89
	v_cvt_pk_bf16_f32 v93, v90, v91
	v_cvt_pk_bf16_f32 v94, v80, v81
	v_cvt_pk_bf16_f32 v95, v82, v83
	v_add_u32_e32 v84, 32, v147
	v_mad_i64_i32 v[86:87], s[28:29], v84, s63, v[114:115]
	v_lshl_add_u64 v[86:87], v[86:87], 0, v[116:117]
	global_store_dwordx4 v[86:87], v[92:95], off sc1
	s_waitcnt lgkmcnt(0)
	v_mul_f32_e32 v76, v152, v76
	v_mul_f32_e32 v77, v152, v77
	v_mul_f32_e32 v78, v152, v78
	v_mul_f32_e32 v79, v152, v79
	v_mul_f32_e32 v68, v152, v68
	v_mul_f32_e32 v69, v152, v69
	v_mul_f32_e32 v70, v152, v70
	v_mul_f32_e32 v71, v152, v71
	v_mul_f32_e32 v72, v152, v72
	v_mul_f32_e32 v73, v152, v73
	v_mul_f32_e32 v74, v152, v74
	v_mul_f32_e32 v75, v152, v75
	v_mul_f32_e32 v64, v152, v64
	v_mul_f32_e32 v65, v152, v65
	v_mul_f32_e32 v66, v152, v66
	v_mul_f32_e32 v67, v152, v67
	ds_read_b32 v150, v148 offset:512
	v_mul_f32_e32 v72, v76, v72
	v_mul_f32_e32 v73, v77, v73
	v_mul_f32_e32 v74, v78, v74
	v_mul_f32_e32 v75, v79, v75
	v_mul_f32_e32 v64, v68, v64
	v_mul_f32_e32 v65, v69, v65
	v_mul_f32_e32 v66, v70, v66
	v_mul_f32_e32 v67, v71, v67
	v_mul_f32_e32 v76, 0xbfb8aa3b, v76
	v_mul_f32_e32 v77, 0xbfb8aa3b, v77
	v_mul_f32_e32 v78, 0xbfb8aa3b, v78
	v_mul_f32_e32 v79, 0xbfb8aa3b, v79
	v_mul_f32_e32 v68, 0xbfb8aa3b, v68
	v_mul_f32_e32 v69, 0xbfb8aa3b, v69
	v_mul_f32_e32 v70, 0xbfb8aa3b, v70
	v_mul_f32_e32 v71, 0xbfb8aa3b, v71
	v_exp_f32_e32 v76, v76
	v_exp_f32_e32 v77, v77
	v_exp_f32_e32 v78, v78
	v_exp_f32_e32 v79, v79
	v_exp_f32_e32 v68, v68
	v_exp_f32_e32 v69, v69
	v_exp_f32_e32 v70, v70
	v_exp_f32_e32 v71, v71
	v_add_f32_e32 v76, 1.0, v76
	v_add_f32_e32 v77, 1.0, v77
	v_add_f32_e32 v78, 1.0, v78
	v_add_f32_e32 v79, 1.0, v79
	v_add_f32_e32 v68, 1.0, v68
	v_add_f32_e32 v69, 1.0, v69
	v_add_f32_e32 v70, 1.0, v70
	v_add_f32_e32 v71, 1.0, v71
	v_rcp_f32_e32 v76, v76
	v_rcp_f32_e32 v77, v77
	v_rcp_f32_e32 v78, v78
	v_rcp_f32_e32 v79, v79
	v_rcp_f32_e32 v68, v68
	v_rcp_f32_e32 v69, v69
	v_rcp_f32_e32 v70, v70
	v_rcp_f32_e32 v71, v71
	v_mul_f32_e32 v72, v72, v76
	v_mul_f32_e32 v73, v73, v77
	v_mul_f32_e32 v74, v74, v78
	v_mul_f32_e32 v75, v75, v79
	v_mul_f32_e32 v64, v64, v68
	v_mul_f32_e32 v65, v65, v69
	v_mul_f32_e32 v66, v66, v70
	v_mul_f32_e32 v67, v67, v71
	v_cvt_pk_bf16_f32 v76, v72, v73
	v_cvt_pk_bf16_f32 v77, v74, v75
	v_cvt_pk_bf16_f32 v78, v64, v65
	v_cvt_pk_bf16_f32 v79, v66, v67
	v_add_u32_e32 v68, 48, v147
	v_mad_i64_i32 v[70:71], s[28:29], v68, s63, v[114:115]
	v_lshl_add_u64 v[70:71], v[70:71], 0, v[116:117]
	global_store_dwordx4 v[70:71], v[76:79], off sc1
	s_waitcnt lgkmcnt(0)
	v_mul_f32_e32 v60, v150, v60
	v_mul_f32_e32 v61, v150, v61
	v_mul_f32_e32 v62, v150, v62
	v_mul_f32_e32 v63, v150, v63
	v_mul_f32_e32 v52, v150, v52
	v_mul_f32_e32 v53, v150, v53
	v_mul_f32_e32 v54, v150, v54
	v_mul_f32_e32 v55, v150, v55
	v_mul_f32_e32 v56, v150, v56
	v_mul_f32_e32 v57, v150, v57
	v_mul_f32_e32 v58, v150, v58
	v_mul_f32_e32 v59, v150, v59
	v_mul_f32_e32 v48, v150, v48
	v_mul_f32_e32 v49, v150, v49
	v_mul_f32_e32 v50, v150, v50
	v_mul_f32_e32 v51, v150, v51
	ds_read_b32 v152, v148 offset:576
	v_mul_f32_e32 v56, v60, v56
	v_mul_f32_e32 v57, v61, v57
	v_mul_f32_e32 v58, v62, v58
	v_mul_f32_e32 v59, v63, v59
	v_mul_f32_e32 v48, v52, v48
	v_mul_f32_e32 v49, v53, v49
	v_mul_f32_e32 v50, v54, v50
	v_mul_f32_e32 v51, v55, v51
	v_mul_f32_e32 v60, 0xbfb8aa3b, v60
	v_mul_f32_e32 v61, 0xbfb8aa3b, v61
	v_mul_f32_e32 v62, 0xbfb8aa3b, v62
	v_mul_f32_e32 v63, 0xbfb8aa3b, v63
	v_mul_f32_e32 v52, 0xbfb8aa3b, v52
	v_mul_f32_e32 v53, 0xbfb8aa3b, v53
	v_mul_f32_e32 v54, 0xbfb8aa3b, v54
	v_mul_f32_e32 v55, 0xbfb8aa3b, v55
	v_exp_f32_e32 v60, v60
	v_exp_f32_e32 v61, v61
	v_exp_f32_e32 v62, v62
	v_exp_f32_e32 v63, v63
	v_exp_f32_e32 v52, v52
	v_exp_f32_e32 v53, v53
	v_exp_f32_e32 v54, v54
	v_exp_f32_e32 v55, v55
	v_add_f32_e32 v60, 1.0, v60
	v_add_f32_e32 v61, 1.0, v61
	v_add_f32_e32 v62, 1.0, v62
	v_add_f32_e32 v63, 1.0, v63
	v_add_f32_e32 v52, 1.0, v52
	v_add_f32_e32 v53, 1.0, v53
	v_add_f32_e32 v54, 1.0, v54
	v_add_f32_e32 v55, 1.0, v55
	v_rcp_f32_e32 v60, v60
	v_rcp_f32_e32 v61, v61
	v_rcp_f32_e32 v62, v62
	v_rcp_f32_e32 v63, v63
	v_rcp_f32_e32 v52, v52
	v_rcp_f32_e32 v53, v53
	v_rcp_f32_e32 v54, v54
	v_rcp_f32_e32 v55, v55
	v_mul_f32_e32 v56, v56, v60
	v_mul_f32_e32 v57, v57, v61
	v_mul_f32_e32 v58, v58, v62
	v_mul_f32_e32 v59, v59, v63
	v_mul_f32_e32 v48, v48, v52
	v_mul_f32_e32 v49, v49, v53
	v_mul_f32_e32 v50, v50, v54
	v_mul_f32_e32 v51, v51, v55
	v_cvt_pk_bf16_f32 v60, v56, v57
	v_cvt_pk_bf16_f32 v61, v58, v59
	v_cvt_pk_bf16_f32 v62, v48, v49
	v_cvt_pk_bf16_f32 v63, v50, v51
	v_add_u32_e32 v52, 128, v147
	v_mad_i64_i32 v[54:55], s[28:29], v52, s63, v[114:115]
	v_lshl_add_u64 v[54:55], v[54:55], 0, v[116:117]
	global_store_dwordx4 v[54:55], v[60:63], off sc1
	s_waitcnt lgkmcnt(0)
; __device__ __forceinline__ unsigned cvt_pk_bf16(float lo, float hi) { unsigned r; asm volatile("v_cvt_pk_bf16_f32 %0, %1, %2" : "=v"(r) : "v"(lo), "v"(hi)); return r; }
; #define PG8_BAR __builtin_amdgcn_s_barrier()
;     __device__ __forceinline__ void operator()(const f32x4 (&acc)[2][2][4][2], const Unit& u, int wr, int wc, int fr, int fq, const PG8_LAS float* tab) const {
;     ...
;             for (int m = 0; m < 4; ++m) { const int row = row0 + ai * HALF + m * 16;
;                 const float rs = tab[ai * HALF + wr * 64 + m * 16 + fr];
;                 float hv[8];
; #pragma unroll
;                 for (int n = 0; n < 2; ++n)
; #pragma unroll
;                     for (int j = 0; j < 4; ++j) { const float g = acc[ai][0][m][n][j] * rs, up = acc[ai][1][m][n][j] * rs;
;                         const float e = __builtin_amdgcn_exp2f(g * -1.4426950408889634f);
;                         hv[4 * n + j] = g * up * __builtin_amdgcn_rcpf(1.0f + e); }
;                 u32x4 w; w.x = cvt_pk_bf16(hv[0], hv[1]); w.y = cvt_pk_bf16(hv[2], hv[3]); w.z = cvt_pk_bf16(hv[4], hv[5]); w.w = cvt_pk_bf16(hv[6], hv[7]);
;                 *(u32x4*)(H + (size_t)row * ldh + col0) = w; }
; template <class Epi, class Sched, bool ALIGN_EPI, bool SP2, int KK, int LDA, int APN>
; __device__ __forceinline__ void gemm_phase(PG8_LAS unsigned char* lds, const Gemm g, const Sched& S, const Epi& E, const int wid) {
;     ...
;         if constexpr (ALIGN_EPI) { if (wr == 1) PG8_BAR; }
	v_mul_f32_e32 v44, v152, v44
	v_mul_f32_e32 v45, v152, v45
	v_mul_f32_e32 v46, v152, v46
	v_mul_f32_e32 v47, v152, v47
	v_mul_f32_e32 v36, v152, v36
	v_mul_f32_e32 v37, v152, v37
	v_mul_f32_e32 v38, v152, v38
	v_mul_f32_e32 v39, v152, v39
	v_mul_f32_e32 v40, v152, v40
	v_mul_f32_e32 v41, v152, v41
	v_mul_f32_e32 v42, v152, v42
	v_mul_f32_e32 v43, v152, v43
	v_mul_f32_e32 v32, v152, v32
	v_mul_f32_e32 v33, v152, v33
	v_mul_f32_e32 v34, v152, v34
	v_mul_f32_e32 v35, v152, v35
	ds_read_b32 v150, v148 offset:640
	v_mul_f32_e32 v40, v44, v40
	v_mul_f32_e32 v41, v45, v41
	v_mul_f32_e32 v42, v46, v42
	v_mul_f32_e32 v43, v47, v43
	v_mul_f32_e32 v32, v36, v32
	v_mul_f32_e32 v33, v37, v33
	v_mul_f32_e32 v34, v38, v34
	v_mul_f32_e32 v35, v39, v35
	v_mul_f32_e32 v44, 0xbfb8aa3b, v44
	v_mul_f32_e32 v45, 0xbfb8aa3b, v45
	v_mul_f32_e32 v46, 0xbfb8aa3b, v46
	v_mul_f32_e32 v47, 0xbfb8aa3b, v47
	v_mul_f32_e32 v36, 0xbfb8aa3b, v36
	v_mul_f32_e32 v37, 0xbfb8aa3b, v37
	v_mul_f32_e32 v38, 0xbfb8aa3b, v38
	v_mul_f32_e32 v39, 0xbfb8aa3b, v39
	v_exp_f32_e32 v44, v44
	v_exp_f32_e32 v45, v45
	v_exp_f32_e32 v46, v46
	v_exp_f32_e32 v47, v47
	v_exp_f32_e32 v36, v36
	v_exp_f32_e32 v37, v37
	v_exp_f32_e32 v38, v38
	v_exp_f32_e32 v39, v39
	v_add_f32_e32 v44, 1.0, v44
	v_add_f32_e32 v45, 1.0, v45
	v_add_f32_e32 v46, 1.0, v46
	v_add_f32_e32 v47, 1.0, v47
	v_add_f32_e32 v36, 1.0, v36
	v_add_f32_e32 v37, 1.0, v37
	v_add_f32_e32 v38, 1.0, v38
	v_add_f32_e32 v39, 1.0, v39
	v_rcp_f32_e32 v44, v44
	v_rcp_f32_e32 v45, v45
	v_rcp_f32_e32 v46, v46
	v_rcp_f32_e32 v47, v47
	v_rcp_f32_e32 v36, v36
	v_rcp_f32_e32 v37, v37
	v_rcp_f32_e32 v38, v38
	v_rcp_f32_e32 v39, v39
	v_mul_f32_e32 v40, v40, v44
	v_mul_f32_e32 v41, v41, v45
	v_mul_f32_e32 v42, v42, v46
	v_mul_f32_e32 v43, v43, v47
	v_mul_f32_e32 v32, v32, v36
	v_mul_f32_e32 v33, v33, v37
	v_mul_f32_e32 v34, v34, v38
	v_mul_f32_e32 v35, v35, v39
	v_cvt_pk_bf16_f32 v44, v40, v41
	v_cvt_pk_bf16_f32 v45, v42, v43
	v_cvt_pk_bf16_f32 v46, v32, v33
	v_cvt_pk_bf16_f32 v47, v34, v35
	v_add_u32_e32 v36, 144, v147
	v_mad_i64_i32 v[38:39], s[28:29], v36, s63, v[114:115]
	v_lshl_add_u64 v[38:39], v[38:39], 0, v[116:117]
	global_store_dwordx4 v[38:39], v[44:47], off sc1
	s_waitcnt lgkmcnt(0)
	v_mul_f32_e32 v28, v150, v28
	v_mul_f32_e32 v29, v150, v29
	v_mul_f32_e32 v30, v150, v30
	v_mul_f32_e32 v31, v150, v31
	v_mul_f32_e32 v20, v150, v20
	v_mul_f32_e32 v21, v150, v21
	v_mul_f32_e32 v22, v150, v22
	v_mul_f32_e32 v23, v150, v23
	v_mul_f32_e32 v24, v150, v24
	v_mul_f32_e32 v25, v150, v25
	v_mul_f32_e32 v26, v150, v26
	v_mul_f32_e32 v27, v150, v27
	v_mul_f32_e32 v16, v150, v16
	v_mul_f32_e32 v17, v150, v17
	v_mul_f32_e32 v18, v150, v18
	v_mul_f32_e32 v19, v150, v19
	ds_read_b32 v152, v148 offset:704
	v_mul_f32_e32 v24, v28, v24
	v_mul_f32_e32 v25, v29, v25
	v_mul_f32_e32 v26, v30, v26
	v_mul_f32_e32 v27, v31, v27
	v_mul_f32_e32 v16, v20, v16
	v_mul_f32_e32 v17, v21, v17
	v_mul_f32_e32 v18, v22, v18
	v_mul_f32_e32 v19, v23, v19
	v_mul_f32_e32 v28, 0xbfb8aa3b, v28
	v_mul_f32_e32 v29, 0xbfb8aa3b, v29
	v_mul_f32_e32 v30, 0xbfb8aa3b, v30
	v_mul_f32_e32 v31, 0xbfb8aa3b, v31
	v_mul_f32_e32 v20, 0xbfb8aa3b, v20
	v_mul_f32_e32 v21, 0xbfb8aa3b, v21
	v_mul_f32_e32 v22, 0xbfb8aa3b, v22
	v_mul_f32_e32 v23, 0xbfb8aa3b, v23
	v_exp_f32_e32 v28, v28
	v_exp_f32_e32 v29, v29
	v_exp_f32_e32 v30, v30
	v_exp_f32_e32 v31, v31
	v_exp_f32_e32 v20, v20
	v_exp_f32_e32 v21, v21
	v_exp_f32_e32 v22, v22
	v_exp_f32_e32 v23, v23
	v_add_f32_e32 v28, 1.0, v28
	v_add_f32_e32 v29, 1.0, v29
	v_add_f32_e32 v30, 1.0, v30
	v_add_f32_e32 v31, 1.0, v31
	v_add_f32_e32 v20, 1.0, v20
	v_add_f32_e32 v21, 1.0, v21
	v_add_f32_e32 v22, 1.0, v22
	v_add_f32_e32 v23, 1.0, v23
	v_rcp_f32_e32 v28, v28
	v_rcp_f32_e32 v29, v29
	v_rcp_f32_e32 v30, v30
	v_rcp_f32_e32 v31, v31
	v_rcp_f32_e32 v20, v20
	v_rcp_f32_e32 v21, v21
	v_rcp_f32_e32 v22, v22
	v_rcp_f32_e32 v23, v23
	v_mul_f32_e32 v24, v24, v28
	v_mul_f32_e32 v25, v25, v29
	v_mul_f32_e32 v26, v26, v30
	v_mul_f32_e32 v27, v27, v31
	v_mul_f32_e32 v16, v16, v20
	v_mul_f32_e32 v17, v17, v21
	v_mul_f32_e32 v18, v18, v22
	v_mul_f32_e32 v19, v19, v23
	v_cvt_pk_bf16_f32 v28, v24, v25
	v_cvt_pk_bf16_f32 v29, v26, v27
	v_cvt_pk_bf16_f32 v30, v16, v17
	v_cvt_pk_bf16_f32 v31, v18, v19
	v_add_u32_e32 v20, 160, v147
	v_mad_i64_i32 v[22:23], s[28:29], v20, s63, v[114:115]
	v_lshl_add_u64 v[22:23], v[22:23], 0, v[116:117]
	global_store_dwordx4 v[22:23], v[28:31], off sc1
	s_waitcnt lgkmcnt(0)
	v_mul_f32_e32 v12, v152, v12
	v_mul_f32_e32 v13, v152, v13
	v_mul_f32_e32 v14, v152, v14
	v_mul_f32_e32 v15, v152, v15
	v_mul_f32_e32 v4, v152, v4
	v_mul_f32_e32 v5, v152, v5
	v_mul_f32_e32 v6, v152, v6
	v_mul_f32_e32 v7, v152, v7
	v_mul_f32_e32 v8, v152, v8
	v_mul_f32_e32 v9, v152, v9
	v_mul_f32_e32 v10, v152, v10
	v_mul_f32_e32 v11, v152, v11
	v_mul_f32_e32 v0, v152, v0
	v_mul_f32_e32 v1, v152, v1
	v_mul_f32_e32 v2, v152, v2
	v_mul_f32_e32 v3, v152, v3
	v_mul_f32_e32 v8, v12, v8
	v_mul_f32_e32 v9, v13, v9
	v_mul_f32_e32 v10, v14, v10
	v_mul_f32_e32 v11, v15, v11
	v_mul_f32_e32 v0, v4, v0
	v_mul_f32_e32 v1, v5, v1
	v_mul_f32_e32 v2, v6, v2
	v_mul_f32_e32 v3, v7, v3
	v_mul_f32_e32 v12, 0xbfb8aa3b, v12
	v_mul_f32_e32 v13, 0xbfb8aa3b, v13
	v_mul_f32_e32 v14, 0xbfb8aa3b, v14
	v_mul_f32_e32 v15, 0xbfb8aa3b, v15
	v_mul_f32_e32 v4, 0xbfb8aa3b, v4
	v_mul_f32_e32 v5, 0xbfb8aa3b, v5
	v_mul_f32_e32 v6, 0xbfb8aa3b, v6
	v_mul_f32_e32 v7, 0xbfb8aa3b, v7
	v_exp_f32_e32 v12, v12
	v_exp_f32_e32 v13, v13
	v_exp_f32_e32 v14, v14
	v_exp_f32_e32 v15, v15
	v_exp_f32_e32 v4, v4
	v_exp_f32_e32 v5, v5
	v_exp_f32_e32 v6, v6
	v_exp_f32_e32 v7, v7
	v_add_f32_e32 v12, 1.0, v12
	v_add_f32_e32 v13, 1.0, v13
	v_add_f32_e32 v14, 1.0, v14
	v_add_f32_e32 v15, 1.0, v15
	v_add_f32_e32 v4, 1.0, v4
	v_add_f32_e32 v5, 1.0, v5
	v_add_f32_e32 v6, 1.0, v6
	v_add_f32_e32 v7, 1.0, v7
	v_rcp_f32_e32 v12, v12
	v_rcp_f32_e32 v13, v13
	v_rcp_f32_e32 v14, v14
	v_rcp_f32_e32 v15, v15
	v_rcp_f32_e32 v4, v4
	v_rcp_f32_e32 v5, v5
	v_rcp_f32_e32 v6, v6
	v_rcp_f32_e32 v7, v7
	v_mul_f32_e32 v8, v8, v12
	v_mul_f32_e32 v9, v9, v13
	v_mul_f32_e32 v10, v10, v14
	v_mul_f32_e32 v11, v11, v15
	v_mul_f32_e32 v0, v0, v4
	v_mul_f32_e32 v1, v1, v5
	v_mul_f32_e32 v2, v2, v6
	v_mul_f32_e32 v3, v3, v7
	v_cvt_pk_bf16_f32 v12, v8, v9
	v_cvt_pk_bf16_f32 v13, v10, v11
	v_cvt_pk_bf16_f32 v14, v0, v1
	v_cvt_pk_bf16_f32 v15, v2, v3
	v_add_u32_e32 v4, 176, v147
	v_mad_i64_i32 v[6:7], s[28:29], v4, s63, v[114:115]
	v_lshl_add_u64 v[6:7], v[6:7], 0, v[116:117]
	s_mov_b64 s[28:29], -1
	global_store_dwordx4 v[6:7], v[12:15], off sc1
	s_cbranch_vccnz .LBB0_775
	s_andn2_b64 vcc, exec, s[14:15]
	s_cbranch_vccnz .LBB0_774
	s_barrier
	s_branch .LBB0_774
